# indexer sweeps: relu scale constant of v_pk_mul moved from VGPR pair to SGPR pair s[100:101] (fewer VGPR operand reads)
# speedup vs baseline: 1.0092x; 1.0004x over previous
; #define LAS __attribute__((address_space(3)))
;     constexpr int SHIFT = 24 - 8 * (MODE & 3);
;     const int r32 = lane & 31, hi = lane >> 5, ql = 32 * (wid & 1) + r32;
;     LAS unsigned* hist = (LAS unsigned*)(lds + DS_HIST) + ql;   LAS unsigned short* sel = (LAS unsigned short*)(lds + DS_SEL) + ql * 256; LAS unsigned* cnt = (LAS unsigned*)(lds + DS_CNT) + ql;
;     LAS unsigned* cand = (LAS unsigned*)(lds + DS_CAND) + ql * DS_CAP; LAS unsigned* ccnt = (LAS unsigned*)(lds + DS_CCNT) + ql;
;     LAS const unsigned char* iqb = lds + DS_IQ + ql * 528 + hi * 16; LAS const float* wqb = (LAS const float*)(lds + DS_WQ) + ql;
;     const int kt0 = wid >> 1; const int nit = kt0 <= c ? 2 * ((c - kt0) / 4 + 1) : 0;
;     const float t_lo = bucket_lo((int)pref), t_hi = bucket_lo((int)pref + 1);
;     const bf16_t* ikp = Zb + (size_t)(64 * kt0 + r32) * NZ + ZIK + hi * 8;
;     bf16x8 a0, a1;
;     if (nit > 0) { a0 = *(const bf16x8*)ikp; a1 = *(const bf16x8*)(ikp + 16); }
; #pragma unroll 1
;     for (int it = 0; it < nit; ++it) {
;         const int kt = kt0 + 4 * (it >> 1), kb = it & 1;
;         const int itn = it + 1 < nit ? it + 1 : it;
;         const bf16_t* np = ikp + (size_t)(256 * (itn >> 1) + 32 * (itn & 1)) * NZ; const bf16x8 n0 = *(const bf16x8*)np, n1 = *(const bf16x8*)(np + 16);
;         f32x2v sc2[8];
; #pragma unroll
;         for (int r = 0; r < 8; ++r) sc2[r] = (f32x2v){0.f, 0.f};
;     ...
;         { f32x16 zero16;
; #pragma unroll
;           for (int r = 0; r < 16; ++r) zero16[r] = 0.f;
;           f32x16 dA0, dA1, dB0, dB1; float wA0, wA1, wB0, wB1;
;           SW_MF(0, dA0, dA1, wA0, wA1);
;           SW_MF(1, dB0, dB1, wB0, wB1); __builtin_amdgcn_sched_barrier(0);
;           SW_VA(dA0, dA1, wA0, wA1);    __builtin_amdgcn_sched_barrier(0);
;           SW_MF(2, dA0, dA1, wA0, wA1); __builtin_amdgcn_sched_barrier(0);
;           SW_VA(dB0, dB1, wB0, wB1);    __builtin_amdgcn_sched_barrier(0);
;           SW_MF(3, dB0, dB1, wB0, wB1); __builtin_amdgcn_sched_barrier(0);
;           SW_VA(dA0, dA1, wA0, wA1);    __builtin_amdgcn_sched_barrier(0);
;           SW_VA(dB0, dB1, wB0, wB1); }
.LBB0_979:
	v_add_u32_e32 v1, 0x200, v1
	v_cmp_lt_u32_e32 vcc, s62, v1
	ds_write_b32 v0, v155
	s_or_b64 s[0:1], vcc, s[0:1]
	v_add_u32_e32 v0, 0x800, v0
	s_andn2_b64 exec, exec, s[0:1]
	s_cbranch_execnz .LBB0_979
	s_or_b64 exec, exec, s[0:1]
	s_lshr_b32 s24, s3, 7
	v_mov_b32_e32 v0, s24
	v_sub_co_u32_e64 v0, s[18:19], s2, v0
	s_lshl_b32 s0, s69, 5
	v_readfirstlane_b32 s1, v0
	v_lshl_or_b32 v2, s24, 6, v151
	v_mov_b64_e32 v[0:1], s[36:37]
	v_and_or_b32 v169, s0, 32, v151
	s_lshr_b32 s1, s1, 1
	v_mad_u64_u32 v[0:1], s[2:3], v2, s61, v[0:1]
	v_lshlrev_b32_e32 v154, 1, v152
	v_lshlrev_b32_e32 v171, 2, v169
	s_and_b32 s25, s1, 0x7ffffffe
	v_lshl_add_u64 v[0:1], v[0:1], 0, v[154:155]
	s_mov_b64 s[2:3], 0x1300
	v_add_u32_e32 v230, 0x100, v171
	v_mad_u32_u24 v165, v169, s86, v199
	v_add_u32_e32 v167, s51, v171
	s_add_i32 s25, s25, 2
	v_lshl_add_u64 v[140:141], v[0:1], 0, s[2:3]
	s_and_b64 vcc, exec, s[18:19]
	s_waitcnt lgkmcnt(0)
	s_barrier
	s_cbranch_vccnz .LBB0_983
	global_load_dwordx4 v[76:79], v[140:141], off
	global_load_dwordx4 v[72:75], v[140:141], off offset:32
	s_mov_b32 s2, 0
	v_mov_b32_e32 v117, 0x280
	v_mov_b32_e32 v118, 0x2ff
	v_add_u32_e32 v116, 0xfffe0000, v230
	s_mov_b32 s100, 0x2c800000
	s_mov_b32 s101, 0x2c800000
	ds_read2st64_b32 v[80:81], v167 offset1:1
	ds_read2st64_b32 v[82:83], v167 offset0:2 offset1:3
	ds_read2st64_b32 v[84:85], v167 offset0:4 offset1:5
	ds_read2st64_b32 v[86:87], v167 offset0:6 offset1:7
	ds_read_b128 v[0:3], v165
	ds_read_b128 v[4:7], v165 offset:32
	ds_read_b128 v[8:11], v165 offset:64
	ds_read_b128 v[12:15], v165 offset:96
	s_waitcnt lgkmcnt(4)
	v_mov_b32_e32 v104, v81
	v_mov_b32_e32 v106, v83
	v_mov_b32_e32 v108, v85
	v_mov_b32_e32 v110, v87
	s_waitcnt vmcnt(0) lgkmcnt(0)
	s_cmp_lt_u32 s69, 4
	s_cbranch_scc1 .Lstag_m5
	s_sleep 14
.Lstag_m5:
.Lm5_loop:
	v_mfma_f32_32x32x16_bf16 v[16:31], v[76:79], v[0:3], 0
	v_mfma_f32_32x32x16_bf16 v[16:31], v[72:75], v[4:7], v[16:31]
	ds_read_b128 v[0:3], v165 offset:128
	ds_read_b128 v[4:7], v165 offset:160
	v_mfma_f32_32x32x16_bf16 v[32:47], v[76:79], v[8:11], 0
	v_mfma_f32_32x32x16_bf16 v[32:47], v[72:75], v[12:15], v[32:47]
	ds_read_b128 v[8:11], v165 offset:192
	ds_read_b128 v[12:15], v165 offset:224
	s_add_i32 s1, s2, 1
	s_cmp_lt_u32 s1, s25
	s_cselect_b32 s3, s1, s2
	s_lshl_b32 vcc_lo, s3, 7
	s_and_b32 vcc_lo, vcc_lo, 0x7fffff00
	s_lshl_b32 s3, s3, 5
	s_and_b32 s3, s3, 32
	s_or_b32 s3, vcc_lo, s3
	v_mad_u64_u32 v[114:115], vcc, s3, v223, v[140:141]
	global_load_dwordx4 v[64:67], v[114:115], off
	global_load_dwordx4 v[68:71], v[114:115], off offset:32
	v_pk_mul_f32 v[16:17], v[16:17], s[100:101] clamp
	v_pk_mul_f32 v[18:19], v[18:19], s[100:101] clamp
	v_pk_mul_f32 v[20:21], v[20:21], s[100:101] clamp
	v_pk_mul_f32 v[22:23], v[22:23], s[100:101] clamp
	v_pk_mul_f32 v[24:25], v[24:25], s[100:101] clamp
	v_pk_mul_f32 v[26:27], v[26:27], s[100:101] clamp
	v_pk_mul_f32 v[28:29], v[28:29], s[100:101] clamp
	v_pk_mul_f32 v[30:31], v[30:31], s[100:101] clamp
	v_pk_fma_f32 v[88:89], v[16:17], v[80:81], 0 op_sel_hi:[1,0,0]
	v_pk_fma_f32 v[90:91], v[18:19], v[80:81], 0 op_sel_hi:[1,0,0]
	v_pk_fma_f32 v[92:93], v[20:21], v[80:81], 0 op_sel_hi:[1,0,0]
	v_pk_fma_f32 v[94:95], v[22:23], v[80:81], 0 op_sel_hi:[1,0,0]
	v_pk_fma_f32 v[96:97], v[24:25], v[80:81], 0 op_sel_hi:[1,0,0]
	v_pk_fma_f32 v[98:99], v[26:27], v[80:81], 0 op_sel_hi:[1,0,0]
	v_pk_fma_f32 v[100:101], v[28:29], v[80:81], 0 op_sel_hi:[1,0,0]
	v_pk_fma_f32 v[102:103], v[30:31], v[80:81], 0 op_sel_hi:[1,0,0]
	s_waitcnt lgkmcnt(2)
	v_mfma_f32_32x32x16_bf16 v[16:31], v[76:79], v[0:3], 0
	v_mfma_f32_32x32x16_bf16 v[16:31], v[72:75], v[4:7], v[16:31]
	ds_read_b128 v[0:3], v165 offset:256
	ds_read_b128 v[4:7], v165 offset:288
	v_pk_mul_f32 v[32:33], v[32:33], s[100:101] clamp
	v_pk_mul_f32 v[34:35], v[34:35], s[100:101] clamp
	v_pk_mul_f32 v[36:37], v[36:37], s[100:101] clamp
	v_pk_mul_f32 v[38:39], v[38:39], s[100:101] clamp
	v_pk_mul_f32 v[40:41], v[40:41], s[100:101] clamp
	v_pk_mul_f32 v[42:43], v[42:43], s[100:101] clamp
	v_pk_mul_f32 v[44:45], v[44:45], s[100:101] clamp
	v_pk_mul_f32 v[46:47], v[46:47], s[100:101] clamp
	v_pk_fma_f32 v[88:89], v[32:33], v[104:105], v[88:89] op_sel_hi:[1,0,1]
	v_pk_fma_f32 v[90:91], v[34:35], v[104:105], v[90:91] op_sel_hi:[1,0,1]
	v_pk_fma_f32 v[92:93], v[36:37], v[104:105], v[92:93] op_sel_hi:[1,0,1]
	v_pk_fma_f32 v[94:95], v[38:39], v[104:105], v[94:95] op_sel_hi:[1,0,1]
	v_pk_fma_f32 v[96:97], v[40:41], v[104:105], v[96:97] op_sel_hi:[1,0,1]
	v_pk_fma_f32 v[98:99], v[42:43], v[104:105], v[98:99] op_sel_hi:[1,0,1]
	v_pk_fma_f32 v[100:101], v[44:45], v[104:105], v[100:101] op_sel_hi:[1,0,1]
	v_pk_fma_f32 v[102:103], v[46:47], v[104:105], v[102:103] op_sel_hi:[1,0,1]
	s_waitcnt lgkmcnt(2)
	v_mfma_f32_32x32x16_bf16 v[32:47], v[76:79], v[8:11], 0
	v_mfma_f32_32x32x16_bf16 v[32:47], v[72:75], v[12:15], v[32:47]
	ds_read_b128 v[8:11], v165 offset:320
	ds_read_b128 v[12:15], v165 offset:352
	v_pk_mul_f32 v[16:17], v[16:17], s[100:101] clamp
	v_pk_mul_f32 v[18:19], v[18:19], s[100:101] clamp
	v_pk_mul_f32 v[20:21], v[20:21], s[100:101] clamp
	v_pk_mul_f32 v[22:23], v[22:23], s[100:101] clamp
	v_pk_mul_f32 v[24:25], v[24:25], s[100:101] clamp
	v_pk_mul_f32 v[26:27], v[26:27], s[100:101] clamp
	v_pk_mul_f32 v[28:29], v[28:29], s[100:101] clamp
	v_pk_mul_f32 v[30:31], v[30:31], s[100:101] clamp
	v_pk_fma_f32 v[88:89], v[16:17], v[82:83], v[88:89] op_sel_hi:[1,0,1]
	v_pk_fma_f32 v[90:91], v[18:19], v[82:83], v[90:91] op_sel_hi:[1,0,1]
	v_pk_fma_f32 v[92:93], v[20:21], v[82:83], v[92:93] op_sel_hi:[1,0,1]
	v_pk_fma_f32 v[94:95], v[22:23], v[82:83], v[94:95] op_sel_hi:[1,0,1]
	v_pk_fma_f32 v[96:97], v[24:25], v[82:83], v[96:97] op_sel_hi:[1,0,1]
	v_pk_fma_f32 v[98:99], v[26:27], v[82:83], v[98:99] op_sel_hi:[1,0,1]
	v_pk_fma_f32 v[100:101], v[28:29], v[82:83], v[100:101] op_sel_hi:[1,0,1]
	v_pk_fma_f32 v[102:103], v[30:31], v[82:83], v[102:103] op_sel_hi:[1,0,1]
	s_waitcnt lgkmcnt(2)
;     ...
;         { f32x16 zero16;
; #pragma unroll
;           for (int r = 0; r < 16; ++r) zero16[r] = 0.f;
;           f32x16 dA0, dA1, dB0, dB1; float wA0, wA1, wB0, wB1;
;           SW_MF(0, dA0, dA1, wA0, wA1);
;           SW_MF(1, dB0, dB1, wB0, wB1); __builtin_amdgcn_sched_barrier(0);
;           SW_VA(dA0, dA1, wA0, wA1);    __builtin_amdgcn_sched_barrier(0);
;           SW_MF(2, dA0, dA1, wA0, wA1); __builtin_amdgcn_sched_barrier(0);
;           SW_VA(dB0, dB1, wB0, wB1);    __builtin_amdgcn_sched_barrier(0);
;           SW_MF(3, dB0, dB1, wB0, wB1); __builtin_amdgcn_sched_barrier(0);
;           SW_VA(dA0, dA1, wA0, wA1);    __builtin_amdgcn_sched_barrier(0);
;           SW_VA(dB0, dB1, wB0, wB1); }
	v_mfma_f32_32x32x16_bf16 v[16:31], v[76:79], v[0:3], 0
	v_mfma_f32_32x32x16_bf16 v[16:31], v[72:75], v[4:7], v[16:31]
	ds_read_b128 v[0:3], v165 offset:384
	ds_read_b128 v[4:7], v165 offset:416
	v_pk_mul_f32 v[32:33], v[32:33], s[100:101] clamp
	v_pk_mul_f32 v[34:35], v[34:35], s[100:101] clamp
	v_pk_mul_f32 v[36:37], v[36:37], s[100:101] clamp
	v_pk_mul_f32 v[38:39], v[38:39], s[100:101] clamp
	v_pk_mul_f32 v[40:41], v[40:41], s[100:101] clamp
	v_pk_mul_f32 v[42:43], v[42:43], s[100:101] clamp
	v_pk_mul_f32 v[44:45], v[44:45], s[100:101] clamp
	v_pk_mul_f32 v[46:47], v[46:47], s[100:101] clamp
	v_pk_fma_f32 v[88:89], v[32:33], v[106:107], v[88:89] op_sel_hi:[1,0,1]
	v_pk_fma_f32 v[90:91], v[34:35], v[106:107], v[90:91] op_sel_hi:[1,0,1]
	v_pk_fma_f32 v[92:93], v[36:37], v[106:107], v[92:93] op_sel_hi:[1,0,1]
	v_pk_fma_f32 v[94:95], v[38:39], v[106:107], v[94:95] op_sel_hi:[1,0,1]
	v_pk_fma_f32 v[96:97], v[40:41], v[106:107], v[96:97] op_sel_hi:[1,0,1]
	v_pk_fma_f32 v[98:99], v[42:43], v[106:107], v[98:99] op_sel_hi:[1,0,1]
	v_pk_fma_f32 v[100:101], v[44:45], v[106:107], v[100:101] op_sel_hi:[1,0,1]
	v_pk_fma_f32 v[102:103], v[46:47], v[106:107], v[102:103] op_sel_hi:[1,0,1]
	s_waitcnt lgkmcnt(2)
	v_mfma_f32_32x32x16_bf16 v[32:47], v[76:79], v[8:11], 0
	v_mfma_f32_32x32x16_bf16 v[32:47], v[72:75], v[12:15], v[32:47]
	ds_read_b128 v[8:11], v165 offset:448
	ds_read_b128 v[12:15], v165 offset:480
	v_pk_mul_f32 v[16:17], v[16:17], s[100:101] clamp
	v_pk_mul_f32 v[18:19], v[18:19], s[100:101] clamp
	v_pk_mul_f32 v[20:21], v[20:21], s[100:101] clamp
	v_pk_mul_f32 v[22:23], v[22:23], s[100:101] clamp
	v_pk_mul_f32 v[24:25], v[24:25], s[100:101] clamp
	v_pk_mul_f32 v[26:27], v[26:27], s[100:101] clamp
	v_pk_mul_f32 v[28:29], v[28:29], s[100:101] clamp
	v_pk_mul_f32 v[30:31], v[30:31], s[100:101] clamp
	v_pk_fma_f32 v[88:89], v[16:17], v[84:85], v[88:89] op_sel_hi:[1,0,1]
	v_pk_fma_f32 v[90:91], v[18:19], v[84:85], v[90:91] op_sel_hi:[1,0,1]
	v_pk_fma_f32 v[92:93], v[20:21], v[84:85], v[92:93] op_sel_hi:[1,0,1]
	v_pk_fma_f32 v[94:95], v[22:23], v[84:85], v[94:95] op_sel_hi:[1,0,1]
	v_pk_fma_f32 v[96:97], v[24:25], v[84:85], v[96:97] op_sel_hi:[1,0,1]
	v_pk_fma_f32 v[98:99], v[26:27], v[84:85], v[98:99] op_sel_hi:[1,0,1]
	v_pk_fma_f32 v[100:101], v[28:29], v[84:85], v[100:101] op_sel_hi:[1,0,1]
	v_pk_fma_f32 v[102:103], v[30:31], v[84:85], v[102:103] op_sel_hi:[1,0,1]
	s_waitcnt lgkmcnt(2)
	v_mfma_f32_32x32x16_bf16 v[16:31], v[76:79], v[0:3], 0
	v_mfma_f32_32x32x16_bf16 v[16:31], v[72:75], v[4:7], v[16:31]
	ds_read_b128 v[0:3], v165
	ds_read_b128 v[4:7], v165 offset:32
	v_pk_mul_f32 v[32:33], v[32:33], s[100:101] clamp
	v_pk_mul_f32 v[34:35], v[34:35], s[100:101] clamp
	v_pk_mul_f32 v[36:37], v[36:37], s[100:101] clamp
	v_pk_mul_f32 v[38:39], v[38:39], s[100:101] clamp
	v_pk_mul_f32 v[40:41], v[40:41], s[100:101] clamp
	v_pk_mul_f32 v[42:43], v[42:43], s[100:101] clamp
	v_pk_mul_f32 v[44:45], v[44:45], s[100:101] clamp
	v_pk_mul_f32 v[46:47], v[46:47], s[100:101] clamp
	v_pk_fma_f32 v[88:89], v[32:33], v[108:109], v[88:89] op_sel_hi:[1,0,1]
	v_pk_fma_f32 v[90:91], v[34:35], v[108:109], v[90:91] op_sel_hi:[1,0,1]
	v_pk_fma_f32 v[92:93], v[36:37], v[108:109], v[92:93] op_sel_hi:[1,0,1]
	v_pk_fma_f32 v[94:95], v[38:39], v[108:109], v[94:95] op_sel_hi:[1,0,1]
	v_pk_fma_f32 v[96:97], v[40:41], v[108:109], v[96:97] op_sel_hi:[1,0,1]
	v_pk_fma_f32 v[98:99], v[42:43], v[108:109], v[98:99] op_sel_hi:[1,0,1]
	v_pk_fma_f32 v[100:101], v[44:45], v[108:109], v[100:101] op_sel_hi:[1,0,1]
	v_pk_fma_f32 v[102:103], v[46:47], v[108:109], v[102:103] op_sel_hi:[1,0,1]
	s_waitcnt lgkmcnt(2)
; __device__ __forceinline__ int bucketf(float f) { const unsigned u = __float_as_uint(f); const int idx = (int)((u >> 20) & 0x7FFu); const int c = min(max(idx - 816, 128), 255); return c ^ (((int)u >> 31) & 255); }
;     ...
;         { f32x16 zero16;
; #pragma unroll
;           for (int r = 0; r < 16; ++r) zero16[r] = 0.f;
;           f32x16 dA0, dA1, dB0, dB1; float wA0, wA1, wB0, wB1;
;           SW_MF(0, dA0, dA1, wA0, wA1);
;           SW_MF(1, dB0, dB1, wB0, wB1); __builtin_amdgcn_sched_barrier(0);
;           SW_VA(dA0, dA1, wA0, wA1);    __builtin_amdgcn_sched_barrier(0);
;           SW_MF(2, dA0, dA1, wA0, wA1); __builtin_amdgcn_sched_barrier(0);
;           SW_VA(dB0, dB1, wB0, wB1);    __builtin_amdgcn_sched_barrier(0);
;           SW_MF(3, dB0, dB1, wB0, wB1); __builtin_amdgcn_sched_barrier(0);
;           SW_VA(dA0, dA1, wA0, wA1);    __builtin_amdgcn_sched_barrier(0);
;           SW_VA(dB0, dB1, wB0, wB1); }
;     ...
;         f32x16 sc;
; #pragma unroll
;         for (int r = 0; r < 16; ++r) sc[r] = sc2[r >> 1][r & 1];
;         const unsigned s0 = (unsigned)(64 * kt + 32 * kb + 4 * hi);
; #pragma unroll
;         for (int r = 0; r < 16; ++r) { const unsigned s = s0 + (unsigned)((r & 3) + 8 * (r >> 2));
;             if (MODE == 5) { __hip_atomic_fetch_add(hist + 64 * bucketf(sc[r]), 1u, __ATOMIC_RELAXED, __HIP_MEMORY_SCOPE_WORKGROUP); continue; }
	v_mfma_f32_32x32x16_bf16 v[32:47], v[76:79], v[8:11], 0
	v_mfma_f32_32x32x16_bf16 v[32:47], v[72:75], v[12:15], v[32:47]
	ds_read_b128 v[8:11], v165 offset:64
	ds_read_b128 v[12:15], v165 offset:96
	v_pk_mul_f32 v[16:17], v[16:17], s[100:101] clamp
	v_pk_mul_f32 v[18:19], v[18:19], s[100:101] clamp
	v_pk_mul_f32 v[20:21], v[20:21], s[100:101] clamp
	v_pk_mul_f32 v[22:23], v[22:23], s[100:101] clamp
	v_pk_mul_f32 v[24:25], v[24:25], s[100:101] clamp
	v_pk_mul_f32 v[26:27], v[26:27], s[100:101] clamp
	v_pk_mul_f32 v[28:29], v[28:29], s[100:101] clamp
	v_pk_mul_f32 v[30:31], v[30:31], s[100:101] clamp
	v_pk_fma_f32 v[88:89], v[16:17], v[86:87], v[88:89] op_sel_hi:[1,0,1]
	v_pk_fma_f32 v[90:91], v[18:19], v[86:87], v[90:91] op_sel_hi:[1,0,1]
	v_pk_fma_f32 v[92:93], v[20:21], v[86:87], v[92:93] op_sel_hi:[1,0,1]
	v_pk_fma_f32 v[94:95], v[22:23], v[86:87], v[94:95] op_sel_hi:[1,0,1]
	v_pk_fma_f32 v[96:97], v[24:25], v[86:87], v[96:97] op_sel_hi:[1,0,1]
	v_pk_fma_f32 v[98:99], v[26:27], v[86:87], v[98:99] op_sel_hi:[1,0,1]
	v_pk_fma_f32 v[100:101], v[28:29], v[86:87], v[100:101] op_sel_hi:[1,0,1]
	v_pk_fma_f32 v[102:103], v[30:31], v[86:87], v[102:103] op_sel_hi:[1,0,1]
	v_pk_mul_f32 v[32:33], v[32:33], s[100:101] clamp
	v_pk_mul_f32 v[34:35], v[34:35], s[100:101] clamp
	v_pk_mul_f32 v[36:37], v[36:37], s[100:101] clamp
	v_pk_mul_f32 v[38:39], v[38:39], s[100:101] clamp
	v_pk_mul_f32 v[40:41], v[40:41], s[100:101] clamp
	v_pk_mul_f32 v[42:43], v[42:43], s[100:101] clamp
	v_pk_mul_f32 v[44:45], v[44:45], s[100:101] clamp
	v_pk_mul_f32 v[46:47], v[46:47], s[100:101] clamp
	v_pk_fma_f32 v[88:89], v[32:33], v[110:111], v[88:89] op_sel_hi:[1,0,1]
	v_pk_fma_f32 v[90:91], v[34:35], v[110:111], v[90:91] op_sel_hi:[1,0,1]
	v_pk_fma_f32 v[92:93], v[36:37], v[110:111], v[92:93] op_sel_hi:[1,0,1]
	v_pk_fma_f32 v[94:95], v[38:39], v[110:111], v[94:95] op_sel_hi:[1,0,1]
	v_pk_fma_f32 v[96:97], v[40:41], v[110:111], v[96:97] op_sel_hi:[1,0,1]
	v_pk_fma_f32 v[98:99], v[42:43], v[110:111], v[98:99] op_sel_hi:[1,0,1]
	v_pk_fma_f32 v[100:101], v[44:45], v[110:111], v[100:101] op_sel_hi:[1,0,1]
	v_pk_fma_f32 v[102:103], v[46:47], v[110:111], v[102:103] op_sel_hi:[1,0,1]
	s_waitcnt lgkmcnt(0)
	v_bfe_u32 v48, v88, 20, 11
	v_ashrrev_i32_e32 v49, 31, v88
	v_med3_u32 v48, v48, v117, v118
	v_bitop3_b32 v48, v48, v49, s56 bitop3:0x78
	v_lshl_add_u32 v48, v48, 8, v116
	ds_add_u32 v48, v222
	v_bfe_u32 v50, v89, 20, 11
	v_ashrrev_i32_e32 v51, 31, v89
	v_med3_u32 v50, v50, v117, v118
	v_bitop3_b32 v50, v50, v51, s56 bitop3:0x78
	v_lshl_add_u32 v50, v50, 8, v116
	ds_add_u32 v50, v222
	v_bfe_u32 v52, v90, 20, 11
	v_ashrrev_i32_e32 v53, 31, v90
	v_med3_u32 v52, v52, v117, v118
	v_bitop3_b32 v52, v52, v53, s56 bitop3:0x78
	v_lshl_add_u32 v52, v52, 8, v116
	ds_add_u32 v52, v222
	v_bfe_u32 v54, v91, 20, 11
	v_ashrrev_i32_e32 v55, 31, v91
	v_med3_u32 v54, v54, v117, v118
	v_bitop3_b32 v54, v54, v55, s56 bitop3:0x78
	v_lshl_add_u32 v54, v54, 8, v116
	ds_add_u32 v54, v222
	v_bfe_u32 v48, v92, 20, 11
	v_ashrrev_i32_e32 v49, 31, v92
	v_med3_u32 v48, v48, v117, v118
	v_bitop3_b32 v48, v48, v49, s56 bitop3:0x78
	v_lshl_add_u32 v48, v48, 8, v116
	ds_add_u32 v48, v222
	v_bfe_u32 v50, v93, 20, 11
	v_ashrrev_i32_e32 v51, 31, v93
	v_med3_u32 v50, v50, v117, v118
	v_bitop3_b32 v50, v50, v51, s56 bitop3:0x78
	v_lshl_add_u32 v50, v50, 8, v116
	ds_add_u32 v50, v222
	v_bfe_u32 v52, v94, 20, 11
	v_ashrrev_i32_e32 v53, 31, v94
	v_med3_u32 v52, v52, v117, v118
	v_bitop3_b32 v52, v52, v53, s56 bitop3:0x78
	v_lshl_add_u32 v52, v52, 8, v116
	ds_add_u32 v52, v222
	v_bfe_u32 v54, v95, 20, 11
	v_ashrrev_i32_e32 v55, 31, v95
	v_med3_u32 v54, v54, v117, v118
	v_bitop3_b32 v54, v54, v55, s56 bitop3:0x78
	v_lshl_add_u32 v54, v54, 8, v116
	ds_add_u32 v54, v222
	v_bfe_u32 v48, v96, 20, 11
	v_ashrrev_i32_e32 v49, 31, v96
	v_med3_u32 v48, v48, v117, v118
	v_bitop3_b32 v48, v48, v49, s56 bitop3:0x78
	v_lshl_add_u32 v48, v48, 8, v116
	ds_add_u32 v48, v222
	v_bfe_u32 v50, v97, 20, 11
	v_ashrrev_i32_e32 v51, 31, v97
	v_med3_u32 v50, v50, v117, v118
	v_bitop3_b32 v50, v50, v51, s56 bitop3:0x78
	v_lshl_add_u32 v50, v50, 8, v116
	ds_add_u32 v50, v222
	v_bfe_u32 v52, v98, 20, 11
	v_ashrrev_i32_e32 v53, 31, v98
	v_med3_u32 v52, v52, v117, v118
	v_bitop3_b32 v52, v52, v53, s56 bitop3:0x78
	v_lshl_add_u32 v52, v52, 8, v116
	ds_add_u32 v52, v222
	v_bfe_u32 v54, v99, 20, 11
	v_ashrrev_i32_e32 v55, 31, v99
	v_med3_u32 v54, v54, v117, v118
	v_bitop3_b32 v54, v54, v55, s56 bitop3:0x78
	v_lshl_add_u32 v54, v54, 8, v116
	ds_add_u32 v54, v222
	v_bfe_u32 v48, v100, 20, 11
	v_ashrrev_i32_e32 v49, 31, v100
	v_med3_u32 v48, v48, v117, v118
	v_bitop3_b32 v48, v48, v49, s56 bitop3:0x78
	v_lshl_add_u32 v48, v48, 8, v116
	ds_add_u32 v48, v222
	v_bfe_u32 v50, v101, 20, 11
	v_ashrrev_i32_e32 v51, 31, v101
	v_med3_u32 v50, v50, v117, v118
	v_bitop3_b32 v50, v50, v51, s56 bitop3:0x78
	v_lshl_add_u32 v50, v50, 8, v116
	ds_add_u32 v50, v222
	v_bfe_u32 v52, v102, 20, 11
	v_ashrrev_i32_e32 v53, 31, v102
	v_med3_u32 v52, v52, v117, v118
	v_bitop3_b32 v52, v52, v53, s56 bitop3:0x78
	v_lshl_add_u32 v52, v52, 8, v116
	ds_add_u32 v52, v222
	v_bfe_u32 v54, v103, 20, 11
	v_ashrrev_i32_e32 v55, 31, v103
	v_med3_u32 v54, v54, v117, v118
	v_bitop3_b32 v54, v54, v55, s56 bitop3:0x78
	v_lshl_add_u32 v54, v54, 8, v116
	ds_add_u32 v54, v222
	s_waitcnt vmcnt(0)
	v_mov_b64_e32 v[76:77], v[64:65]
	v_mov_b64_e32 v[78:79], v[66:67]
	v_mov_b64_e32 v[72:73], v[68:69]
	v_mov_b64_e32 v[74:75], v[70:71]
	s_cmp_lg_u32 s25, s1
	s_mov_b32 s2, s1
	s_cbranch_scc1 .Lm5_loop

; #define LAS __attribute__((address_space(3)))
;     constexpr int SHIFT = 24 - 8 * (MODE & 3);
;     const int r32 = lane & 31, hi = lane >> 5, ql = 32 * (wid & 1) + r32;
;     LAS unsigned* hist = (LAS unsigned*)(lds + DS_HIST) + ql;   LAS unsigned short* sel = (LAS unsigned short*)(lds + DS_SEL) + ql * 256; LAS unsigned* cnt = (LAS unsigned*)(lds + DS_CNT) + ql;
;     LAS unsigned* cand = (LAS unsigned*)(lds + DS_CAND) + ql * DS_CAP; LAS unsigned* ccnt = (LAS unsigned*)(lds + DS_CCNT) + ql;
;     LAS const unsigned char* iqb = lds + DS_IQ + ql * 528 + hi * 16; LAS const float* wqb = (LAS const float*)(lds + DS_WQ) + ql;
;     const int kt0 = wid >> 1; const int nit = kt0 <= c ? 2 * ((c - kt0) / 4 + 1) : 0;
;     const float t_lo = bucket_lo((int)pref), t_hi = bucket_lo((int)pref + 1);
;     const bf16_t* ikp = Zb + (size_t)(64 * kt0 + r32) * NZ + ZIK + hi * 8;
;     bf16x8 a0, a1;
;     if (nit > 0) { a0 = *(const bf16x8*)ikp; a1 = *(const bf16x8*)(ikp + 16); }
; #pragma unroll 1
;     for (int it = 0; it < nit; ++it) {
;         const int kt = kt0 + 4 * (it >> 1), kb = it & 1;
;         const int itn = it + 1 < nit ? it + 1 : it;
;         const bf16_t* np = ikp + (size_t)(256 * (itn >> 1) + 32 * (itn & 1)) * NZ; const bf16x8 n0 = *(const bf16x8*)np, n1 = *(const bf16x8*)(np + 16);
;         f32x2v sc2[8];
; #pragma unroll
;         for (int r = 0; r < 8; ++r) sc2[r] = (f32x2v){0.f, 0.f};
;     ...
;         { f32x16 zero16;
; #pragma unroll
;           for (int r = 0; r < 16; ++r) zero16[r] = 0.f;
;           f32x16 dA0, dA1, dB0, dB1; float wA0, wA1, wB0, wB1;
;           SW_MF(0, dA0, dA1, wA0, wA1);
;           SW_MF(1, dB0, dB1, wB0, wB1); __builtin_amdgcn_sched_barrier(0);
;           SW_VA(dA0, dA1, wA0, wA1);    __builtin_amdgcn_sched_barrier(0);
;           SW_MF(2, dA0, dA1, wA0, wA1); __builtin_amdgcn_sched_barrier(0);
;           SW_VA(dB0, dB1, wB0, wB1);    __builtin_amdgcn_sched_barrier(0);
;           SW_MF(3, dB0, dB1, wB0, wB1); __builtin_amdgcn_sched_barrier(0);
;           SW_VA(dA0, dA1, wA0, wA1);    __builtin_amdgcn_sched_barrier(0);
;           SW_VA(dB0, dB1, wB0, wB1); }
.LBB0_1521:
	s_and_b64 vcc, exec, s[18:19]
	s_cbranch_vccnz .LBB0_1620
	v_lshl_add_u32 v179, v169, 9, s57
	v_add_u32_e32 v180, s94, v171
	v_lshl_add_u32 v169, v169, 10, v200
	v_add_u32_e32 v171, s33, v171
	v_mul_f32_e32 v122, 0x2c800000, v154
	v_mul_f32_e32 v123, 0x2c800000, v178
	s_mov_b32 s18, 0
	s_mov_b32 s100, 0x2c800000
	s_mov_b32 s101, 0x2c800000
	ds_read2st64_b32 v[80:81], v167 offset1:1
	ds_read2st64_b32 v[82:83], v167 offset0:2 offset1:3
	ds_read2st64_b32 v[84:85], v167 offset0:4 offset1:5
	ds_read2st64_b32 v[86:87], v167 offset0:6 offset1:7
	ds_read_b128 v[0:3], v165
	ds_read_b128 v[4:7], v165 offset:32
	ds_read_b128 v[8:11], v165 offset:64
	ds_read_b128 v[12:15], v165 offset:96
	s_waitcnt lgkmcnt(4)
	v_mov_b32_e32 v104, v81
	v_mov_b32_e32 v106, v83
	v_mov_b32_e32 v108, v85
	v_mov_b32_e32 v110, v87
	s_waitcnt vmcnt(0) lgkmcnt(0)
	s_cmp_lt_u32 s69, 4
	s_cbranch_scc1 .Lstag_m6
	s_sleep 14
.Lstag_m6:
.Lm6_loop:
	v_mfma_f32_32x32x16_bf16 v[16:31], v[132:135], v[0:3], 0
	v_mfma_f32_32x32x16_bf16 v[16:31], v[128:131], v[4:7], v[16:31]
	ds_read_b128 v[0:3], v165 offset:128
	ds_read_b128 v[4:7], v165 offset:160
	v_mfma_f32_32x32x16_bf16 v[32:47], v[132:135], v[8:11], 0
	v_mfma_f32_32x32x16_bf16 v[32:47], v[128:131], v[12:15], v[32:47]
	ds_read_b128 v[8:11], v165 offset:192
	ds_read_b128 v[12:15], v165 offset:224
	s_add_i32 s1, s18, 1
	s_cmp_lt_u32 s1, s25
	s_cselect_b32 s3, s1, s18
	s_lshl_b32 vcc_lo, s3, 7
	s_and_b32 vcc_lo, vcc_lo, 0x7fffff00
	s_lshl_b32 s3, s3, 5
	s_and_b32 s3, s3, 32
	s_or_b32 s3, vcc_lo, s3
	v_mad_u64_u32 v[114:115], vcc, s3, v223, v[140:141]
	s_lshr_b32 s0, s18, 1
	s_lshl_b32 s0, s0, 2
	s_add_i32 s0, s0, s24
	s_lshl_b32 s0, s0, 6
	s_and_b32 s2, s18, 1
	s_lshl_b32 s2, s2, 5
	s_or_b32 s0, s0, s2
	v_or_b32_e32 v124, s0, v159
	global_load_dwordx4 v[64:67], v[114:115], off
	global_load_dwordx4 v[68:71], v[114:115], off offset:32
	v_pk_mul_f32 v[16:17], v[16:17], s[100:101] clamp
	v_pk_mul_f32 v[18:19], v[18:19], s[100:101] clamp
	v_pk_mul_f32 v[20:21], v[20:21], s[100:101] clamp
	v_pk_mul_f32 v[22:23], v[22:23], s[100:101] clamp
	v_pk_mul_f32 v[24:25], v[24:25], s[100:101] clamp
	v_pk_mul_f32 v[26:27], v[26:27], s[100:101] clamp
	v_pk_mul_f32 v[28:29], v[28:29], s[100:101] clamp
	v_pk_mul_f32 v[30:31], v[30:31], s[100:101] clamp
	v_pk_fma_f32 v[88:89], v[16:17], v[80:81], 0 op_sel_hi:[1,0,0]
	v_pk_fma_f32 v[90:91], v[18:19], v[80:81], 0 op_sel_hi:[1,0,0]
	v_pk_fma_f32 v[92:93], v[20:21], v[80:81], 0 op_sel_hi:[1,0,0]
	v_pk_fma_f32 v[94:95], v[22:23], v[80:81], 0 op_sel_hi:[1,0,0]
	v_pk_fma_f32 v[96:97], v[24:25], v[80:81], 0 op_sel_hi:[1,0,0]
	v_pk_fma_f32 v[98:99], v[26:27], v[80:81], 0 op_sel_hi:[1,0,0]
	v_pk_fma_f32 v[100:101], v[28:29], v[80:81], 0 op_sel_hi:[1,0,0]
	v_pk_fma_f32 v[102:103], v[30:31], v[80:81], 0 op_sel_hi:[1,0,0]
	s_waitcnt lgkmcnt(2)
	v_mfma_f32_32x32x16_bf16 v[16:31], v[132:135], v[0:3], 0
	v_mfma_f32_32x32x16_bf16 v[16:31], v[128:131], v[4:7], v[16:31]
	ds_read_b128 v[0:3], v165 offset:256
	ds_read_b128 v[4:7], v165 offset:288
	v_pk_mul_f32 v[32:33], v[32:33], s[100:101] clamp
	v_pk_mul_f32 v[34:35], v[34:35], s[100:101] clamp
	v_pk_mul_f32 v[36:37], v[36:37], s[100:101] clamp
	v_pk_mul_f32 v[38:39], v[38:39], s[100:101] clamp
	v_pk_mul_f32 v[40:41], v[40:41], s[100:101] clamp
	v_pk_mul_f32 v[42:43], v[42:43], s[100:101] clamp
	v_pk_mul_f32 v[44:45], v[44:45], s[100:101] clamp
	v_pk_mul_f32 v[46:47], v[46:47], s[100:101] clamp
	v_pk_fma_f32 v[88:89], v[32:33], v[104:105], v[88:89] op_sel_hi:[1,0,1]
	v_pk_fma_f32 v[90:91], v[34:35], v[104:105], v[90:91] op_sel_hi:[1,0,1]
	v_pk_fma_f32 v[92:93], v[36:37], v[104:105], v[92:93] op_sel_hi:[1,0,1]
	v_pk_fma_f32 v[94:95], v[38:39], v[104:105], v[94:95] op_sel_hi:[1,0,1]
	v_pk_fma_f32 v[96:97], v[40:41], v[104:105], v[96:97] op_sel_hi:[1,0,1]
	v_pk_fma_f32 v[98:99], v[42:43], v[104:105], v[98:99] op_sel_hi:[1,0,1]
	v_pk_fma_f32 v[100:101], v[44:45], v[104:105], v[100:101] op_sel_hi:[1,0,1]
	v_pk_fma_f32 v[102:103], v[46:47], v[104:105], v[102:103] op_sel_hi:[1,0,1]
	s_waitcnt lgkmcnt(2)
	v_mfma_f32_32x32x16_bf16 v[32:47], v[132:135], v[8:11], 0
	v_mfma_f32_32x32x16_bf16 v[32:47], v[128:131], v[12:15], v[32:47]
	ds_read_b128 v[8:11], v165 offset:320
	ds_read_b128 v[12:15], v165 offset:352
	v_pk_mul_f32 v[16:17], v[16:17], s[100:101] clamp
	v_pk_mul_f32 v[18:19], v[18:19], s[100:101] clamp
	v_pk_mul_f32 v[20:21], v[20:21], s[100:101] clamp
	v_pk_mul_f32 v[22:23], v[22:23], s[100:101] clamp
	v_pk_mul_f32 v[24:25], v[24:25], s[100:101] clamp
	v_pk_mul_f32 v[26:27], v[26:27], s[100:101] clamp
	v_pk_mul_f32 v[28:29], v[28:29], s[100:101] clamp
	v_pk_mul_f32 v[30:31], v[30:31], s[100:101] clamp
	v_pk_fma_f32 v[88:89], v[16:17], v[82:83], v[88:89] op_sel_hi:[1,0,1]
	v_pk_fma_f32 v[90:91], v[18:19], v[82:83], v[90:91] op_sel_hi:[1,0,1]
	v_pk_fma_f32 v[92:93], v[20:21], v[82:83], v[92:93] op_sel_hi:[1,0,1]
	v_pk_fma_f32 v[94:95], v[22:23], v[82:83], v[94:95] op_sel_hi:[1,0,1]
	v_pk_fma_f32 v[96:97], v[24:25], v[82:83], v[96:97] op_sel_hi:[1,0,1]
	v_pk_fma_f32 v[98:99], v[26:27], v[82:83], v[98:99] op_sel_hi:[1,0,1]
	v_pk_fma_f32 v[100:101], v[28:29], v[82:83], v[100:101] op_sel_hi:[1,0,1]
	v_pk_fma_f32 v[102:103], v[30:31], v[82:83], v[102:103] op_sel_hi:[1,0,1]
	s_waitcnt lgkmcnt(2)
; __device__ __forceinline__ unsigned sortable(float f) { const unsigned u = __float_as_uint(f); return u ^ ((unsigned)((int)u >> 31) | 0x80000000u); }
; __device__ __forceinline__ int bucketf(float f) { const unsigned u = __float_as_uint(f); const int idx = (int)((u >> 20) & 0x7FFu); const int c = min(max(idx - 816, 128), 255); return c ^ (((int)u >> 31) & 255); }
;     ...
;         { f32x16 zero16;
; #pragma unroll
;           for (int r = 0; r < 16; ++r) zero16[r] = 0.f;
;           f32x16 dA0, dA1, dB0, dB1; float wA0, wA1, wB0, wB1;
;           SW_MF(0, dA0, dA1, wA0, wA1);
;           SW_MF(1, dB0, dB1, wB0, wB1); __builtin_amdgcn_sched_barrier(0);
;           SW_VA(dA0, dA1, wA0, wA1);    __builtin_amdgcn_sched_barrier(0);
;           SW_MF(2, dA0, dA1, wA0, wA1); __builtin_amdgcn_sched_barrier(0);
;           SW_VA(dB0, dB1, wB0, wB1);    __builtin_amdgcn_sched_barrier(0);
;           SW_MF(3, dB0, dB1, wB0, wB1); __builtin_amdgcn_sched_barrier(0);
;           SW_VA(dA0, dA1, wA0, wA1);    __builtin_amdgcn_sched_barrier(0);
;           SW_VA(dB0, dB1, wB0, wB1); }
;     ...
;         f32x16 sc;
; #pragma unroll
;         for (int r = 0; r < 16; ++r) sc[r] = sc2[r >> 1][r & 1];
;         const unsigned s0 = (unsigned)(64 * kt + 32 * kb + 4 * hi);
; #pragma unroll
;         for (int r = 0; r < 16; ++r) { const unsigned s = s0 + (unsigned)((r & 3) + 8 * (r >> 2));
;             if (MODE == 5) { __hip_atomic_fetch_add(hist + 64 * bucketf(sc[r]), 1u, __ATOMIC_RELAXED, __HIP_MEMORY_SCOPE_WORKGROUP); continue; }
;             if (MODE == 6) {
;                 if (sc[r] >= t_hi) { const unsigned pos = __hip_atomic_fetch_add(cnt, 1u, __ATOMIC_RELAXED, __HIP_MEMORY_SCOPE_WORKGROUP); sel[pos & 255u] = (unsigned short)s; }
;                 else if (sc[r] >= t_lo) { const unsigned key = (sortable(sc[r]) & 0xFFFFE000u) | (8191u - s);
;                     const unsigned pos = __hip_atomic_fetch_add(ccnt, 1u, __ATOMIC_RELAXED, __HIP_MEMORY_SCOPE_WORKGROUP); cand[pos & (DS_CAP - 1)] = key; }
	v_mfma_f32_32x32x16_bf16 v[16:31], v[132:135], v[0:3], 0
	v_mfma_f32_32x32x16_bf16 v[16:31], v[128:131], v[4:7], v[16:31]
	ds_read_b128 v[0:3], v165 offset:384
	ds_read_b128 v[4:7], v165 offset:416
	v_pk_mul_f32 v[32:33], v[32:33], s[100:101] clamp
	v_pk_mul_f32 v[34:35], v[34:35], s[100:101] clamp
	v_pk_mul_f32 v[36:37], v[36:37], s[100:101] clamp
	v_pk_mul_f32 v[38:39], v[38:39], s[100:101] clamp
	v_pk_mul_f32 v[40:41], v[40:41], s[100:101] clamp
	v_pk_mul_f32 v[42:43], v[42:43], s[100:101] clamp
	v_pk_mul_f32 v[44:45], v[44:45], s[100:101] clamp
	v_pk_mul_f32 v[46:47], v[46:47], s[100:101] clamp
	v_pk_fma_f32 v[88:89], v[32:33], v[106:107], v[88:89] op_sel_hi:[1,0,1]
	v_pk_fma_f32 v[90:91], v[34:35], v[106:107], v[90:91] op_sel_hi:[1,0,1]
	v_pk_fma_f32 v[92:93], v[36:37], v[106:107], v[92:93] op_sel_hi:[1,0,1]
	v_pk_fma_f32 v[94:95], v[38:39], v[106:107], v[94:95] op_sel_hi:[1,0,1]
	v_pk_fma_f32 v[96:97], v[40:41], v[106:107], v[96:97] op_sel_hi:[1,0,1]
	v_pk_fma_f32 v[98:99], v[42:43], v[106:107], v[98:99] op_sel_hi:[1,0,1]
	v_pk_fma_f32 v[100:101], v[44:45], v[106:107], v[100:101] op_sel_hi:[1,0,1]
	v_pk_fma_f32 v[102:103], v[46:47], v[106:107], v[102:103] op_sel_hi:[1,0,1]
	s_waitcnt lgkmcnt(2)
	v_mfma_f32_32x32x16_bf16 v[32:47], v[132:135], v[8:11], 0
	v_mfma_f32_32x32x16_bf16 v[32:47], v[128:131], v[12:15], v[32:47]
	ds_read_b128 v[8:11], v165 offset:448
	ds_read_b128 v[12:15], v165 offset:480
	v_pk_mul_f32 v[16:17], v[16:17], s[100:101] clamp
	v_pk_mul_f32 v[18:19], v[18:19], s[100:101] clamp
	v_pk_mul_f32 v[20:21], v[20:21], s[100:101] clamp
	v_pk_mul_f32 v[22:23], v[22:23], s[100:101] clamp
	v_pk_mul_f32 v[24:25], v[24:25], s[100:101] clamp
	v_pk_mul_f32 v[26:27], v[26:27], s[100:101] clamp
	v_pk_mul_f32 v[28:29], v[28:29], s[100:101] clamp
	v_pk_mul_f32 v[30:31], v[30:31], s[100:101] clamp
	v_pk_fma_f32 v[88:89], v[16:17], v[84:85], v[88:89] op_sel_hi:[1,0,1]
	v_pk_fma_f32 v[90:91], v[18:19], v[84:85], v[90:91] op_sel_hi:[1,0,1]
	v_pk_fma_f32 v[92:93], v[20:21], v[84:85], v[92:93] op_sel_hi:[1,0,1]
	v_pk_fma_f32 v[94:95], v[22:23], v[84:85], v[94:95] op_sel_hi:[1,0,1]
	v_pk_fma_f32 v[96:97], v[24:25], v[84:85], v[96:97] op_sel_hi:[1,0,1]
	v_pk_fma_f32 v[98:99], v[26:27], v[84:85], v[98:99] op_sel_hi:[1,0,1]
	v_pk_fma_f32 v[100:101], v[28:29], v[84:85], v[100:101] op_sel_hi:[1,0,1]
	v_pk_fma_f32 v[102:103], v[30:31], v[84:85], v[102:103] op_sel_hi:[1,0,1]
	s_waitcnt lgkmcnt(2)
	v_mfma_f32_32x32x16_bf16 v[16:31], v[132:135], v[0:3], 0
	v_mfma_f32_32x32x16_bf16 v[16:31], v[128:131], v[4:7], v[16:31]
	ds_read_b128 v[0:3], v165
	ds_read_b128 v[4:7], v165 offset:32
	v_pk_mul_f32 v[32:33], v[32:33], s[100:101] clamp
	v_pk_mul_f32 v[34:35], v[34:35], s[100:101] clamp
	v_pk_mul_f32 v[36:37], v[36:37], s[100:101] clamp
	v_pk_mul_f32 v[38:39], v[38:39], s[100:101] clamp
	v_pk_mul_f32 v[40:41], v[40:41], s[100:101] clamp
	v_pk_mul_f32 v[42:43], v[42:43], s[100:101] clamp
	v_pk_mul_f32 v[44:45], v[44:45], s[100:101] clamp
	v_pk_mul_f32 v[46:47], v[46:47], s[100:101] clamp
	v_pk_fma_f32 v[88:89], v[32:33], v[108:109], v[88:89] op_sel_hi:[1,0,1]
	v_pk_fma_f32 v[90:91], v[34:35], v[108:109], v[90:91] op_sel_hi:[1,0,1]
	v_pk_fma_f32 v[92:93], v[36:37], v[108:109], v[92:93] op_sel_hi:[1,0,1]
	v_pk_fma_f32 v[94:95], v[38:39], v[108:109], v[94:95] op_sel_hi:[1,0,1]
	v_pk_fma_f32 v[96:97], v[40:41], v[108:109], v[96:97] op_sel_hi:[1,0,1]
	v_pk_fma_f32 v[98:99], v[42:43], v[108:109], v[98:99] op_sel_hi:[1,0,1]
	v_pk_fma_f32 v[100:101], v[44:45], v[108:109], v[100:101] op_sel_hi:[1,0,1]
	v_pk_fma_f32 v[102:103], v[46:47], v[108:109], v[102:103] op_sel_hi:[1,0,1]
	s_waitcnt lgkmcnt(2)
	v_mfma_f32_32x32x16_bf16 v[32:47], v[132:135], v[8:11], 0
	v_mfma_f32_32x32x16_bf16 v[32:47], v[128:131], v[12:15], v[32:47]
	ds_read_b128 v[8:11], v165 offset:64
	ds_read_b128 v[12:15], v165 offset:96
	v_pk_mul_f32 v[16:17], v[16:17], s[100:101] clamp
	v_pk_mul_f32 v[18:19], v[18:19], s[100:101] clamp
	v_pk_mul_f32 v[20:21], v[20:21], s[100:101] clamp
	v_pk_mul_f32 v[22:23], v[22:23], s[100:101] clamp
	v_pk_mul_f32 v[24:25], v[24:25], s[100:101] clamp
	v_pk_mul_f32 v[26:27], v[26:27], s[100:101] clamp
	v_pk_mul_f32 v[28:29], v[28:29], s[100:101] clamp
	v_pk_mul_f32 v[30:31], v[30:31], s[100:101] clamp
	v_pk_fma_f32 v[88:89], v[16:17], v[86:87], v[88:89] op_sel_hi:[1,0,1]
	v_pk_fma_f32 v[90:91], v[18:19], v[86:87], v[90:91] op_sel_hi:[1,0,1]
	v_pk_fma_f32 v[92:93], v[20:21], v[86:87], v[92:93] op_sel_hi:[1,0,1]
	v_pk_fma_f32 v[94:95], v[22:23], v[86:87], v[94:95] op_sel_hi:[1,0,1]
	v_pk_fma_f32 v[96:97], v[24:25], v[86:87], v[96:97] op_sel_hi:[1,0,1]
	v_pk_fma_f32 v[98:99], v[26:27], v[86:87], v[98:99] op_sel_hi:[1,0,1]
	v_pk_fma_f32 v[100:101], v[28:29], v[86:87], v[100:101] op_sel_hi:[1,0,1]
	v_pk_fma_f32 v[102:103], v[30:31], v[86:87], v[102:103] op_sel_hi:[1,0,1]
	v_pk_mul_f32 v[32:33], v[32:33], s[100:101] clamp
	v_pk_mul_f32 v[34:35], v[34:35], s[100:101] clamp
	v_pk_mul_f32 v[36:37], v[36:37], s[100:101] clamp
	v_pk_mul_f32 v[38:39], v[38:39], s[100:101] clamp
	v_pk_mul_f32 v[40:41], v[40:41], s[100:101] clamp
	v_pk_mul_f32 v[42:43], v[42:43], s[100:101] clamp
	v_pk_mul_f32 v[44:45], v[44:45], s[100:101] clamp
	v_pk_mul_f32 v[46:47], v[46:47], s[100:101] clamp
	v_pk_fma_f32 v[88:89], v[32:33], v[110:111], v[88:89] op_sel_hi:[1,0,1]
	v_pk_fma_f32 v[90:91], v[34:35], v[110:111], v[90:91] op_sel_hi:[1,0,1]
	v_pk_fma_f32 v[92:93], v[36:37], v[110:111], v[92:93] op_sel_hi:[1,0,1]
	v_pk_fma_f32 v[94:95], v[38:39], v[110:111], v[94:95] op_sel_hi:[1,0,1]
	v_pk_fma_f32 v[96:97], v[40:41], v[110:111], v[96:97] op_sel_hi:[1,0,1]
	v_pk_fma_f32 v[98:99], v[42:43], v[110:111], v[98:99] op_sel_hi:[1,0,1]
	v_pk_fma_f32 v[100:101], v[44:45], v[110:111], v[100:101] op_sel_hi:[1,0,1]
	v_pk_fma_f32 v[102:103], v[46:47], v[110:111], v[102:103] op_sel_hi:[1,0,1]
	s_waitcnt lgkmcnt(0)
	v_cmp_ge_f32_e64 s[40:41], v88, v122
	v_cmp_ge_f32_e64 s[42:43], v88, v123
	v_mov_b32_e32 v18, v124
	s_andn2_b64 s[42:43], s[42:43], s[40:41]
	s_mov_b64 exec, s[40:41]
	ds_add_rtn_u32 v16, v180, v222
	s_mov_b64 exec, s[42:43]
	ds_add_rtn_u32 v16, v171, v222
	s_mov_b64 exec, -1
	v_cmp_ge_f32_e64 s[44:45], v89, v122
	v_cmp_ge_f32_e64 s[22:23], v89, v123
	v_or_b32_e32 v19, 1, v124
	s_andn2_b64 s[22:23], s[22:23], s[44:45]
	s_mov_b64 exec, s[44:45]
	ds_add_rtn_u32 v17, v180, v222
	s_mov_b64 exec, s[22:23]
	ds_add_rtn_u32 v17, v171, v222
	s_mov_b64 exec, -1
	v_cmp_ge_f32_e64 s[20:21], v90, v122
	v_cmp_ge_f32_e64 s[2:3], v90, v123
	v_or_b32_e32 v24, 2, v124
	s_andn2_b64 s[2:3], s[2:3], s[20:21]
	s_mov_b64 exec, s[20:21]
	ds_add_rtn_u32 v23, v180, v222
	s_mov_b64 exec, s[2:3]
	ds_add_rtn_u32 v23, v171, v222
	s_mov_b64 exec, -1
	s_waitcnt lgkmcnt(4)
	v_and_b32_e32 v16, 0xff, v16
	s_mov_b64 exec, s[40:41]
	v_lshl_add_u32 v20, v16, 1, v179
	ds_write_b16 v20, v18
	s_mov_b64 exec, s[42:43]
	s_cbranch_execz .Lm6_nb0
; __device__ __forceinline__ unsigned sortable(float f) { const unsigned u = __float_as_uint(f); return u ^ ((unsigned)((int)u >> 31) | 0x80000000u); }
;     ...
;                 else if (sc[r] >= t_lo) { const unsigned key = (sortable(sc[r]) & 0xFFFFE000u) | (8191u - s);
;                     const unsigned pos = __hip_atomic_fetch_add(ccnt, 1u, __ATOMIC_RELAXED, __HIP_MEMORY_SCOPE_WORKGROUP); cand[pos & (DS_CAP - 1)] = key; }
	v_ashrrev_i32_e32 v22, 31, v88
	v_sub_u32_e32 v18, 0x1fff, v18
	v_lshl_add_u32 v20, v16, 2, v169
	v_bitop3_b32 v21, v22, v88, s64 bitop3:0x36
	v_and_or_b32 v21, v21, s65, v18
	ds_write_b32 v20, v21

; #define LAS __attribute__((address_space(3)))
; __global__ void __launch_bounds__(512, 2) mega(Params p) {
;     extern __shared__ __attribute__((aligned(16))) unsigned char lds_raw[];
;     LAS unsigned char* lds = (LAS unsigned char*)lds_raw;
	.amdhsa_kernel _Z4mega6Params
		.amdhsa_group_segment_fixed_size 256
		.amdhsa_private_segment_fixed_size 0
		.amdhsa_kernarg_size 480
		.amdhsa_user_sgpr_count 2
		.amdhsa_user_sgpr_dispatch_ptr 0
		.amdhsa_user_sgpr_queue_ptr 0
		.amdhsa_user_sgpr_kernarg_segment_ptr 1
		.amdhsa_user_sgpr_dispatch_id 0
		.amdhsa_user_sgpr_kernarg_preload_length 0
		.amdhsa_user_sgpr_kernarg_preload_offset 0
		.amdhsa_user_sgpr_private_segment_size 0
		.amdhsa_uses_dynamic_stack 0
		.amdhsa_enable_private_segment 0
		.amdhsa_system_sgpr_workgroup_id_x 1
		.amdhsa_system_sgpr_workgroup_id_y 1
		.amdhsa_system_sgpr_workgroup_id_z 1
		.amdhsa_system_sgpr_workgroup_info 0
		.amdhsa_system_vgpr_workitem_id 2
		.amdhsa_next_free_vgpr 241
		.amdhsa_next_free_sgpr 102
		.amdhsa_accum_offset 244
		.amdhsa_reserve_vcc 1
		.amdhsa_float_round_mode_32 0
		.amdhsa_float_round_mode_16_64 0
		.amdhsa_float_denorm_mode_32 3
		.amdhsa_float_denorm_mode_16_64 3
		.amdhsa_dx10_clamp 1
		.amdhsa_ieee_mode 1
		.amdhsa_fp16_overflow 0
		.amdhsa_tg_split 0
		.amdhsa_exception_fp_ieee_invalid_op 0
		.amdhsa_exception_fp_denorm_src 0
		.amdhsa_exception_fp_ieee_div_zero 0
		.amdhsa_exception_fp_ieee_overflow 0
		.amdhsa_exception_fp_ieee_underflow 0
		.amdhsa_exception_fp_ieee_inexact 0
		.amdhsa_exception_int_div_zero 0
	.end_amdhsa_kernel

; __global__ void __launch_bounds__(512, 2) mega(Params p) {
amdhsa.kernels:
  - .agpr_count:     0
    .args:
      - .offset:         0
        .size:           224
        .value_kind:     by_value
      - .offset:         224
        .size:           4
        .value_kind:     hidden_block_count_x
      - .offset:         228
        .size:           4
        .value_kind:     hidden_block_count_y
      - .offset:         232
        .size:           4
        .value_kind:     hidden_block_count_z
      - .offset:         236
        .size:           2
        .value_kind:     hidden_group_size_x
      - .offset:         238
        .size:           2
        .value_kind:     hidden_group_size_y
      - .offset:         240
        .size:           2
        .value_kind:     hidden_group_size_z
      - .offset:         242
        .size:           2
        .value_kind:     hidden_remainder_x
      - .offset:         244
        .size:           2
        .value_kind:     hidden_remainder_y
      - .offset:         246
        .size:           2
        .value_kind:     hidden_remainder_z
      - .offset:         264
        .size:           8
        .value_kind:     hidden_global_offset_x
      - .offset:         272
        .size:           8
        .value_kind:     hidden_global_offset_y
      - .offset:         280
        .size:           8
        .value_kind:     hidden_global_offset_z
      - .offset:         288
        .size:           2
        .value_kind:     hidden_grid_dims
      - .offset:         312
        .size:           8
        .value_kind:     hidden_multigrid_sync_arg
      - .offset:         344
        .size:           4
        .value_kind:     hidden_dynamic_lds_size
    .group_segment_fixed_size: 256
    .kernarg_segment_align: 8
    .kernarg_segment_size: 480
    .language:       OpenCL C
    .language_version:
      - 2
      - 0
    .max_flat_workgroup_size: 512
    .name:           _Z4mega6Params
    .private_segment_fixed_size: 0
    .sgpr_count:     108
    .sgpr_spill_count: 29
    .symbol:         _Z4mega6Params.kd
    .uniform_work_group_size: 1
    .uses_dynamic_stack: false
    .vgpr_count:     241
    .vgpr_spill_count: 0
    .wavefront_size: 64
